# static s_setprio 1 for the younger wave half (waves 4-7) during the attention phase, reset before the conv branch
# baseline (speedup 1.0000x reference)
; #define LAS __attribute__((address_space(3)))
; __device__ __forceinline__ void unit(const Ctx& C, int xq, int idx, LAS unsigned char* lds) {
;     ...
;     const int pi = 16 * (q >> 4) + 8 * ((q >> 2) & 1) + 4 * ((q >> 3) & 1) + (q & 3);
;     const int koff = mp * KSL + pi * 144 + hi * 16;
;     const int voff = KBUF + q * 144 + hi * 16;
;     const LAS float* tab = (const LAS float*)(lds + TAB_OFF) + h * 256;
;     const float b15 = tab[0];
; __global__ void __launch_bounds__(512, 2) mk_fwd(Args a) {
;     ...
;         float d1 = 0.f, d2 = 0.f;
;         for (int i = 0; i < 64; ++i) { d1 += a.in[I_LQ1][i] * a.in[I_LK1][i]; d2 += a.in[I_LQ2][i] * a.in[I_LK2][i]; }
;         att::Ctx C{PROJ, KC, VTC, VTP, VTN, OOB, a.in[I_SUB], __expf(d1) - __expf(d2) + 0.2f};
;         LAS int* misc = (LAS int*)(lds + MISC_OFF);
;         __syncthreads();
.LBB0_475:
	s_add_u32 s4, s54, s0
	s_addc_u32 s5, s55, s1
	global_load_dwordx4 v[4:7], v2, s[4:5]
	global_load_dwordx4 v[8:11], v2, s[4:5] offset:16
	s_add_u32 s4, s56, s0
	s_addc_u32 s5, s57, s1
	global_load_dwordx4 v[12:15], v2, s[4:5]
	global_load_dwordx4 v[16:19], v2, s[4:5] offset:16
	s_add_u32 s4, s58, s0
	s_addc_u32 s5, s59, s1
	global_load_dwordx4 v[20:23], v2, s[4:5]
	global_load_dwordx4 v[24:27], v2, s[4:5] offset:16
	s_add_u32 s4, s60, s0
	s_addc_u32 s5, s61, s1
	global_load_dwordx4 v[28:31], v2, s[4:5]
	global_load_dwordx4 v[32:35], v2, s[4:5] offset:16
	s_add_u32 s0, s0, 32
	s_addc_u32 s1, s1, 0
	s_cmpk_eq_i32 s0, 0x100
	s_waitcnt vmcnt(7)
	v_mov_b32_e32 v36, v4
	v_mov_b32_e32 v4, v6
	s_waitcnt vmcnt(6)
	v_mov_b32_e32 v6, v8
	v_mov_b32_e32 v8, v10
	s_waitcnt vmcnt(5)
	v_mov_b32_e32 v10, v12
	v_mov_b32_e32 v12, v14
	s_waitcnt vmcnt(3)
	v_mov_b32_e32 v37, v20
	v_mov_b32_e32 v20, v5
	v_mov_b32_e32 v5, v22
	v_mov_b32_e32 v22, v7
	s_waitcnt vmcnt(2)
	v_mov_b32_e32 v7, v24
	v_mov_b32_e32 v24, v9
	v_mov_b32_e32 v9, v26
	v_mov_b32_e32 v26, v11
	s_waitcnt vmcnt(1)
	v_mov_b32_e32 v11, v28
	v_mov_b32_e32 v28, v13
	v_pk_fma_f32 v[0:1], v[36:37], v[10:11], v[0:1]
	v_mov_b32_e32 v13, v30
	v_pk_fma_f32 v[0:1], v[20:21], v[28:29], v[0:1]
	v_mov_b32_e32 v30, v15
	v_pk_fma_f32 v[0:1], v[4:5], v[12:13], v[0:1]
	v_mov_b32_e32 v14, v16
	s_waitcnt vmcnt(0)
	v_mov_b32_e32 v15, v32
	v_pk_fma_f32 v[0:1], v[22:23], v[30:31], v[0:1]
	v_mov_b32_e32 v32, v17
	v_pk_fma_f32 v[0:1], v[6:7], v[14:15], v[0:1]
	v_mov_b32_e32 v16, v18
	v_mov_b32_e32 v17, v34
	v_pk_fma_f32 v[0:1], v[24:25], v[32:33], v[0:1]
	v_mov_b32_e32 v34, v19
	v_pk_fma_f32 v[0:1], v[8:9], v[16:17], v[0:1]
	s_nop 0
	v_pk_fma_f32 v[0:1], v[26:27], v[34:35], v[0:1]
	s_cbranch_scc0 .LBB0_475
	v_mul_f32_e32 v0, 0x3fb8aa3b, v0
	v_mul_f32_e32 v1, 0x3fb8aa3b, v1
	v_exp_f32_e32 v0, v0
	v_exp_f32_e32 v1, v1
	v_lshlrev_b32_e32 v2, 4, v179
	v_and_b32_e32 v2, 0x70, v2
	v_add_u32_e32 v3, 0, v2
	v_lshlrev_b32_e32 v2, 1, v179
	v_lshrrev_b32_e32 v8, 1, v179
	v_sub_f32_e32 v0, v0, v1
	v_add_u32_e32 v1, 0x200, v179
	v_and_b32_e32 v2, 8, v2
	v_and_b32_e32 v8, 4, v8
	v_and_b32_e32 v9, 19, v179
	v_lshrrev_b32_e32 v204, 4, v1
	v_lshrrev_b32_e32 v205, 3, v1
	v_bfe_i32 v1, v179, 3, 1
	s_movk_i32 s0, 0x90
	v_or3_b32 v2, v9, v2, v8
	v_lshlrev_b32_e32 v184, 4, v178
	s_add_u32 s9, s68, 0x1ab00200
	v_lshrrev_b32_e32 v177, 4, v179
	v_lshrrev_b32_e32 v203, 3, v179
	v_and_b32_e32 v1, 0x2400, v1
	v_mad_u32_u24 v206, v2, s0, v184
	v_mul_u32_u24_e32 v2, 0x90, v201
	s_addc_u32 s72, s69, 0
	v_add_f32_e32 v182, 0x3e4ccccd, v0
	v_lshlrev_b32_e32 v0, 3, v178
	v_mov_b32_e32 v185, 0
	v_add_u32_e32 v1, v3, v1
	v_mul_u32_u24_e32 v4, 0x90, v177
	v_mul_u32_u24_e32 v5, 0x90, v203
	v_mul_u32_u24_e32 v6, 0x90, v204
	v_mul_u32_u24_e32 v7, 0x90, v205
	v_add3_u32 v207, v2, v184, 0
	v_lshlrev_b32_e32 v2, 2, v178
	s_add_u32 s73, s68, 0x3d80800
	v_and_b32_e32 v186, 0x78, v221
	s_mov_b32 s5, 0
	v_add_u32_e32 v208, 0xd800, v207
	v_lshlrev_b32_e32 v209, 9, v178
	v_lshl_add_u64 v[188:189], s[62:63], 0, v[184:185]
	v_mov_b32_e32 v183, v182
	v_sub_u32_e32 v210, v0, v201
	s_addc_u32 s76, s69, 0
	s_add_i32 s77, 0, 0x26000
	v_lshlrev_b32_e32 v190, 1, v0
	s_add_i32 s78, 0, 0x242fc
	s_mov_b32 s8, 0x3e38aa3b
	v_lshlrev_b32_e32 v192, 1, v2
	v_mov_b32_e32 v211, 0x358637bd
	v_add_u32_e32 v212, v1, v4
	v_add_u32_e32 v213, v3, v5
	v_add_u32_e32 v214, v1, v6
	v_add_u32_e32 v215, v3, v7
	s_mov_b32 s79, 0
	s_waitcnt lgkmcnt(0)
	s_barrier
	v_readfirstlane_b32 s0, v179
	s_nop 3
	s_cmp_ge_u32 s0, 0x100
	s_cbranch_scc0 .Lp2_prio_done
	s_setprio 1
.Lp2_prio_done:
	s_branch .LBB0_478
.LBB0_477:
	s_add_i32 s79, s79, 1
	s_cmp_eq_u32 s79, 8
	s_cbranch_scc1 .LBB0_554

; __global__ void __launch_bounds__(512, 2) mk_fwd(Args a) {
;     ...
;         const float* cwm = a.in[I_CW];
;         for (int it = bx * 512 + tid; it < (MTOT / 8) * 128; it += G * 512) {
;             const int cg8 = it & 127, r0 = (it >> 7) * 8, ch = cg8 * 8;
;             const bool samp = r0 >= MP; const int t0 = samp ? ((r0 - MP) & 63) : (r0 & (SEQ - 1));
.LBB0_554:
	s_setprio 0
	v_lshl_add_u32 v52, s2, 9, v179
	s_mov_b32 s0, 0x44000
	v_cmp_gt_i32_e32 vcc, s0, v52
	s_and_saveexec_b64 s[8:9], vcc
	s_cbranch_execz .LBB0_587
	s_add_u32 s10, s30, 0x11060000
	s_addc_u32 s11, s31, 0
	s_lshl_b32 s14, s3, 9
	v_lshl_add_u32 v53, s2, 12, v221
	s_lshl_b32 s15, s3, 12
	s_mov_b64 s[36:37], 0
	s_movk_i32 s33, 0x4000
	s_movk_i32 s52, 0x3fff
	s_movk_i32 s53, 0xff8
	v_mov_b32_e32 v54, 0xff8
	v_mov_b32_e32 v45, 0
	s_mov_b64 s[40:41], 0x1000
	s_mov_b64 s[42:43], 0x2000
	s_movk_i32 s54, 0x1000
	s_movk_i32 s55, 0x4800
	s_movk_i32 s56, 0xffd
	s_mov_b32 s57, 0x43fff
	s_branch .LBB0_557
